# MLP-up GEMM: first half of the epilogue (row groups 0-3) overlapped with the last K-iteration's final MFMA phase; hand-written in-place epilogue
# speedup vs baseline: 1.0023x; 1.0023x over previous
; #define PG8_STAGE(bufoff, gbase, voff) do { _Pragma("unroll") for (int _i = 0; _i < 2; ++_i) \
;         __builtin_amdgcn_global_load_lds((const unsigned*)((const char*)(gbase) + (voff)[_i]), (LAS unsigned*)(lds + (bufoff) + ldsw + _i * 8192), 16, 0, 0); } while (0)
; #define PG8_LDA(dst, b, h) do { _Pragma("unroll") for (int m = 0; m < 4; ++m) _Pragma("unroll") for (int k = 0; k < 2; ++k) dst[m][k] = *(const LAS bf16x8*)(lds + PG8_SA(b, h) + aoff + m * 2048 + k * 1024); } while (0)
; #define PG8_LDB(dst, b, h) do { _Pragma("unroll") for (int n = 0; n < 2; ++n) _Pragma("unroll") for (int k = 0; k < 2; ++k) dst[n][k] = *(const LAS bf16x8*)(lds + PG8_SB(b, h) + boff + n * 2048 + k * 1024); } while (0)
; #define PG8_MMA(ai, bj, At, Bt) do { __builtin_amdgcn_s_setprio(1); _Pragma("unroll") for (int m = 0; m < 4; ++m) _Pragma("unroll") for (int n = 0; n < 2; ++n) _Pragma("unroll") for (int k = 0; k < 2; ++k) \
;         acc[ai][bj][m][n] = __builtin_amdgcn_mfma_f32_16x16x32_bf16(Bt[n][k], At[m][k], acc[ai][bj][m][n], 0, 0, 0); __builtin_amdgcn_s_setprio(0); } while (0)
; #define PG8_WAIT_V(n) asm volatile("s_waitcnt vmcnt(" #n ")" ::: "memory")
; #define PG8_WAIT_L(n) asm volatile("s_waitcnt lgkmcnt(" #n ")" ::: "memory")
; #define PG8_BAR __builtin_amdgcn_s_barrier()
; #define PG8_SCHED __builtin_amdgcn_sched_barrier(0)
;     ...
;             PG8_LDB(B0, 0, 0); PG8_LDB(B1, 0, 1); PG8_SCHED; PG8_LDA(At, 0, 0); PG8_STAGE(PG8_SA(1, 1), a1 + hA, voffA);
;             PG8_WAIT_V(8); PG8_WAIT_L(0); PG8_BAR; PG8_MMA(0, 0, At, B0); PG8_MMA(0, 1, At, B1); PG8_BAR; PG8_SCHED;
;             PG8_LDA(At, 0, 1); PG8_STAGE(PG8_SB(0, 0), b2, voffB); PG8_STAGE(PG8_SB(0, 1), b2 + hB, voffB); PG8_STAGE(PG8_SA(0, 0), a2, voffA);
;             PG8_WAIT_V(8); PG8_WAIT_L(0); PG8_BAR; PG8_MMA(1, 0, At, B0); PG8_MMA(1, 1, At, B1); PG8_BAR; PG8_SCHED;
.LBB0_299:
	s_add_u32 s72, s44, s52
	s_addc_u32 s73, s45, s53
	s_add_u32 s76, s72, 0x100
	s_addc_u32 s77, s73, 0
	s_add_u32 s74, s79, s52
	s_addc_u32 s75, s80, s53
	s_add_u32 s72, s72, 0x180
	s_addc_u32 s73, s73, 0
	s_add_i32 s82, 0, 0x10000
	s_add_i32 s89, 0, 0x14000
	v_add_u32_e32 v144, s82, v193
	v_add_u32_e32 v184, s89, v193
	ds_read_b128 v[132:135], v144
	ds_read_b128 v[136:139], v144 offset:1024
	ds_read_b128 v[140:143], v144 offset:2048
	ds_read_b128 v[144:147], v144 offset:3072
	ds_read_b128 v[148:151], v184
	ds_read_b128 v[176:179], v184 offset:1024
	ds_read_b128 v[180:183], v184 offset:2048
	ds_read_b128 v[184:187], v184 offset:3072
	s_cmpk_eq_i32 s52, 0x700
	s_cselect_b32 s73, s78, s73
	s_cselect_b32 s72, s55, s72
	s_cselect_b32 s75, s27, s75
	s_cselect_b32 s74, s54, s74
	s_cselect_b32 s77, s3, s77
	s_cselect_b32 s76, s29, s76
	v_lshl_add_u64 v[196:197], v[128:129], 0, s[52:53]
	s_add_i32 m0, s6, 0xc000
	ds_read_b128 v[188:191], v198
	ds_read_b128 v[200:203], v198 offset:1024
	ds_read_b128 v[208:211], v198 offset:2048
	ds_read_b128 v[214:217], v198 offset:3072
	ds_read_b128 v[230:233], v198 offset:4096
	ds_read_b128 v[234:237], v198 offset:5120
	ds_read_b128 v[238:241], v198 offset:6144
	ds_read_b128 v[242:245], v198 offset:7168
	global_load_lds_dwordx4 v[196:197], off
	v_lshl_add_u64 v[196:197], v[130:131], 0, s[52:53]
	s_add_i32 m0, s6, 0xe000
	s_nop 0
	global_load_lds_dwordx4 v[196:197], off
	s_waitcnt vmcnt(8)
	s_waitcnt lgkmcnt(0)
	s_barrier
	s_setprio 1
	s_waitcnt lgkmcnt(0)
	v_mfma_f32_16x16x32_bf16 v[124:127], v[132:135], v[188:191], v[124:127]
	v_mfma_f32_16x16x32_bf16 v[120:123], v[140:143], v[188:191], v[120:123]
	v_mfma_f32_16x16x32_bf16 v[108:111], v[132:135], v[208:211], v[108:111]
	v_mfma_f32_16x16x32_bf16 v[104:107], v[140:143], v[208:211], v[104:107]
	v_mfma_f32_16x16x32_bf16 v[92:95], v[132:135], v[230:233], v[92:95]
	v_mfma_f32_16x16x32_bf16 v[88:91], v[140:143], v[230:233], v[88:91]
	v_mfma_f32_16x16x32_bf16 v[76:79], v[132:135], v[238:241], v[76:79]
	v_mfma_f32_16x16x32_bf16 v[72:75], v[140:143], v[238:241], v[72:75]
	v_mfma_f32_16x16x32_bf16 v[124:127], v[136:139], v[200:203], v[124:127]
	v_mfma_f32_16x16x32_bf16 v[120:123], v[144:147], v[200:203], v[120:123]
	v_mfma_f32_16x16x32_bf16 v[108:111], v[136:139], v[214:217], v[108:111]
	v_mfma_f32_16x16x32_bf16 v[104:107], v[144:147], v[214:217], v[104:107]
	v_mfma_f32_16x16x32_bf16 v[92:95], v[136:139], v[234:237], v[92:95]
	v_mfma_f32_16x16x32_bf16 v[88:91], v[144:147], v[234:237], v[88:91]
	v_mfma_f32_16x16x32_bf16 v[76:79], v[136:139], v[242:245], v[76:79]
	v_mfma_f32_16x16x32_bf16 v[72:75], v[144:147], v[242:245], v[72:75]
	s_setprio 0
	s_setprio 1
	v_mfma_f32_16x16x32_bf16 v[116:119], v[148:151], v[188:191], v[116:119]
	v_mfma_f32_16x16x32_bf16 v[112:115], v[180:183], v[188:191], v[112:115]
	v_mfma_f32_16x16x32_bf16 v[100:103], v[148:151], v[208:211], v[100:103]
	v_mfma_f32_16x16x32_bf16 v[96:99], v[180:183], v[208:211], v[96:99]
	v_mfma_f32_16x16x32_bf16 v[84:87], v[148:151], v[230:233], v[84:87]
	v_mfma_f32_16x16x32_bf16 v[80:83], v[180:183], v[230:233], v[80:83]
	v_mfma_f32_16x16x32_bf16 v[68:71], v[148:151], v[238:241], v[68:71]
	v_mfma_f32_16x16x32_bf16 v[64:67], v[180:183], v[238:241], v[64:67]
	v_mfma_f32_16x16x32_bf16 v[116:119], v[176:179], v[200:203], v[116:119]
	v_mfma_f32_16x16x32_bf16 v[112:115], v[184:187], v[200:203], v[112:115]
	v_mfma_f32_16x16x32_bf16 v[100:103], v[176:179], v[214:217], v[100:103]
	v_mfma_f32_16x16x32_bf16 v[96:99], v[184:187], v[214:217], v[96:99]
	v_mfma_f32_16x16x32_bf16 v[84:87], v[176:179], v[234:237], v[84:87]
	v_mfma_f32_16x16x32_bf16 v[80:83], v[184:187], v[234:237], v[80:83]
	v_mfma_f32_16x16x32_bf16 v[68:71], v[176:179], v[242:245], v[68:71]
	v_mfma_f32_16x16x32_bf16 v[64:67], v[184:187], v[242:245], v[64:67]
	s_setprio 0
	s_barrier
	s_add_i32 s82, s82, s5
	v_lshl_add_u64 v[196:197], s[74:75], 0, v[156:157]
	s_mov_b32 m0, s82
	ds_read_b128 v[188:191], v198 offset:16384
	ds_read_b128 v[200:203], v198 offset:17408
	ds_read_b128 v[208:211], v198 offset:18432
	ds_read_b128 v[214:217], v198 offset:19456
	ds_read_b128 v[230:233], v198 offset:20480
	ds_read_b128 v[234:237], v198 offset:21504
	ds_read_b128 v[238:241], v198 offset:22528
	ds_read_b128 v[242:245], v198 offset:23552
	global_load_lds_dwordx4 v[196:197], off
	s_add_i32 m0, s82, 0x2000
	s_add_u32 s82, s74, 0x40000
	v_lshl_add_u64 v[204:205], s[74:75], 0, v[168:169]
	s_addc_u32 s83, s75, 0
	s_add_i32 s89, s89, s5
	global_load_lds_dwordx4 v[204:205], off
	v_lshl_add_u64 v[206:207], s[82:83], 0, v[156:157]
	s_mov_b32 m0, s89
	s_nop 0
	global_load_lds_dwordx4 v[206:207], off
	v_lshl_add_u64 v[206:207], s[82:83], 0, v[168:169]
	s_add_i32 m0, s89, 0x2000
	s_nop 0
	global_load_lds_dwordx4 v[206:207], off
	v_lshl_add_u64 v[206:207], s[76:77], 0, v[152:153]
	s_mov_b32 m0, s6
	s_nop 0
	global_load_lds_dwordx4 v[206:207], off
	v_lshl_add_u64 v[206:207], s[76:77], 0, v[154:155]
	s_mov_b32 m0, s7
	s_nop 0
	global_load_lds_dwordx4 v[206:207], off
	s_waitcnt vmcnt(8)
	s_waitcnt lgkmcnt(0)
	s_barrier
; #define PG8_STAGE(bufoff, gbase, voff) do { _Pragma("unroll") for (int _i = 0; _i < 2; ++_i) \
;         __builtin_amdgcn_global_load_lds((const unsigned*)((const char*)(gbase) + (voff)[_i]), (LAS unsigned*)(lds + (bufoff) + ldsw + _i * 8192), 16, 0, 0); } while (0)
; #define PG8_LDA(dst, b, h) do { _Pragma("unroll") for (int m = 0; m < 4; ++m) _Pragma("unroll") for (int k = 0; k < 2; ++k) dst[m][k] = *(const LAS bf16x8*)(lds + PG8_SA(b, h) + aoff + m * 2048 + k * 1024); } while (0)
; #define PG8_LDB(dst, b, h) do { _Pragma("unroll") for (int n = 0; n < 2; ++n) _Pragma("unroll") for (int k = 0; k < 2; ++k) dst[n][k] = *(const LAS bf16x8*)(lds + PG8_SB(b, h) + boff + n * 2048 + k * 1024); } while (0)
; #define PG8_MMA(ai, bj, At, Bt) do { __builtin_amdgcn_s_setprio(1); _Pragma("unroll") for (int m = 0; m < 4; ++m) _Pragma("unroll") for (int n = 0; n < 2; ++n) _Pragma("unroll") for (int k = 0; k < 2; ++k) \
;         acc[ai][bj][m][n] = __builtin_amdgcn_mfma_f32_16x16x32_bf16(Bt[n][k], At[m][k], acc[ai][bj][m][n], 0, 0, 0); __builtin_amdgcn_s_setprio(0); } while (0)
; #define PG8_WAIT_V(n) asm volatile("s_waitcnt vmcnt(" #n ")" ::: "memory")
; #define PG8_WAIT_L(n) asm volatile("s_waitcnt lgkmcnt(" #n ")" ::: "memory")
; #define PG8_BAR __builtin_amdgcn_s_barrier()
; #define PG8_SCHED __builtin_amdgcn_sched_barrier(0)
;     ...
;             PG8_LDB(B0, 1, 0); PG8_LDB(B1, 1, 1); PG8_SCHED; PG8_LDA(At, 1, 0); PG8_STAGE(PG8_SA(0, 1), a2 + hA, voffA);
;             PG8_WAIT_V(8); PG8_WAIT_L(0); PG8_BAR; PG8_MMA(0, 0, At, B0); PG8_MMA(0, 1, At, B1); PG8_BAR; PG8_SCHED;
;             PG8_LDA(At, 1, 1); PG8_STAGE(PG8_SB(1, 0), b3, voffB); PG8_STAGE(PG8_SB(1, 1), b3 + hB, voffB); PG8_STAGE(PG8_SA(1, 0), a3, voffA);
;             PG8_WAIT_V(8); PG8_WAIT_L(0); PG8_BAR; PG8_MMA(1, 0, At, B0); PG8_MMA(1, 1, At, B1); PG8_BAR; PG8_SCHED;
	s_setprio 1
	s_waitcnt lgkmcnt(0)
	v_mfma_f32_16x16x32_bf16 v[60:63], v[132:135], v[188:191], v[60:63]
	v_mfma_f32_16x16x32_bf16 v[56:59], v[140:143], v[188:191], v[56:59]
	v_mfma_f32_16x16x32_bf16 v[44:47], v[132:135], v[208:211], v[44:47]
	v_mfma_f32_16x16x32_bf16 v[40:43], v[140:143], v[208:211], v[40:43]
	v_mfma_f32_16x16x32_bf16 v[28:31], v[132:135], v[230:233], v[28:31]
	v_mfma_f32_16x16x32_bf16 v[24:27], v[140:143], v[230:233], v[24:27]
	v_mfma_f32_16x16x32_bf16 v[12:15], v[132:135], v[238:241], v[12:15]
	v_mfma_f32_16x16x32_bf16 v[8:11], v[140:143], v[238:241], v[8:11]
	v_mfma_f32_16x16x32_bf16 v[60:63], v[136:139], v[200:203], v[60:63]
	v_mfma_f32_16x16x32_bf16 v[56:59], v[144:147], v[200:203], v[56:59]
	v_mfma_f32_16x16x32_bf16 v[44:47], v[136:139], v[214:217], v[44:47]
	v_mfma_f32_16x16x32_bf16 v[40:43], v[144:147], v[214:217], v[40:43]
	v_mfma_f32_16x16x32_bf16 v[28:31], v[136:139], v[234:237], v[28:31]
	v_mfma_f32_16x16x32_bf16 v[24:27], v[144:147], v[234:237], v[24:27]
	v_mfma_f32_16x16x32_bf16 v[12:15], v[136:139], v[242:245], v[12:15]
	v_mfma_f32_16x16x32_bf16 v[8:11], v[144:147], v[242:245], v[8:11]
	s_setprio 0
	s_setprio 1
	v_mfma_f32_16x16x32_bf16 v[52:55], v[148:151], v[188:191], v[52:55]
	v_mfma_f32_16x16x32_bf16 v[48:51], v[180:183], v[188:191], v[48:51]
	v_mfma_f32_16x16x32_bf16 v[36:39], v[148:151], v[208:211], v[36:39]
	v_mfma_f32_16x16x32_bf16 v[32:35], v[180:183], v[208:211], v[32:35]
	v_mfma_f32_16x16x32_bf16 v[20:23], v[148:151], v[230:233], v[20:23]
	v_mfma_f32_16x16x32_bf16 v[16:19], v[180:183], v[230:233], v[16:19]
	v_mfma_f32_16x16x32_bf16 v[4:7], v[148:151], v[238:241], v[4:7]
	v_mfma_f32_16x16x32_bf16 v[0:3], v[180:183], v[238:241], v[0:3]
	v_mfma_f32_16x16x32_bf16 v[52:55], v[176:179], v[200:203], v[52:55]
	v_mfma_f32_16x16x32_bf16 v[48:51], v[184:187], v[200:203], v[48:51]
	v_mfma_f32_16x16x32_bf16 v[36:39], v[176:179], v[214:217], v[36:39]
	v_mfma_f32_16x16x32_bf16 v[32:35], v[184:187], v[214:217], v[32:35]
	v_mfma_f32_16x16x32_bf16 v[20:23], v[176:179], v[234:237], v[20:23]
	v_mfma_f32_16x16x32_bf16 v[16:19], v[184:187], v[234:237], v[16:19]
	v_mfma_f32_16x16x32_bf16 v[4:7], v[176:179], v[242:245], v[4:7]
	v_mfma_f32_16x16x32_bf16 v[0:3], v[184:187], v[242:245], v[0:3]
	s_setprio 0
	s_barrier
	s_cmpk_eq_i32 s52, 0x700
	s_cbranch_scc1 .Lup_last
	s_add_i32 s82, 0, 0x18000
	s_add_i32 s83, 0, 0x1c000
	v_add_u32_e32 v144, s82, v193
	v_add_u32_e32 v184, s83, v193
	ds_read_b128 v[132:135], v144
	ds_read_b128 v[136:139], v144 offset:1024
	ds_read_b128 v[140:143], v144 offset:2048
	ds_read_b128 v[144:147], v144 offset:3072
	ds_read_b128 v[148:151], v184
	ds_read_b128 v[176:179], v184 offset:1024
	ds_read_b128 v[180:183], v184 offset:2048
	ds_read_b128 v[184:187], v184 offset:3072
	s_add_u32 s76, s76, 0x40000
	s_addc_u32 s77, s77, 0
	s_mov_b32 m0, s8
	v_lshl_add_u64 v[206:207], s[76:77], 0, v[152:153]
	ds_read_b128 v[188:191], v198 offset:32768
	ds_read_b128 v[200:203], v198 offset:33792
	ds_read_b128 v[208:211], v198 offset:34816
	ds_read_b128 v[214:217], v198 offset:35840
	ds_read_b128 v[230:233], v198 offset:36864
	ds_read_b128 v[234:237], v198 offset:37888
	ds_read_b128 v[238:241], v198 offset:38912
	ds_read_b128 v[242:245], v198 offset:39936
	global_load_lds_dwordx4 v[206:207], off
	v_lshl_add_u64 v[206:207], s[76:77], 0, v[154:155]
	s_mov_b32 m0, s9
	s_nop 0
	global_load_lds_dwordx4 v[206:207], off
	s_waitcnt vmcnt(8)
	s_waitcnt lgkmcnt(0)
	s_barrier
	s_setprio 1
	s_waitcnt lgkmcnt(0)
	v_mfma_f32_16x16x32_bf16 v[124:127], v[132:135], v[188:191], v[124:127]
	v_mfma_f32_16x16x32_bf16 v[120:123], v[140:143], v[188:191], v[120:123]
	v_mfma_f32_16x16x32_bf16 v[108:111], v[132:135], v[208:211], v[108:111]
	v_mfma_f32_16x16x32_bf16 v[104:107], v[140:143], v[208:211], v[104:107]
	v_mfma_f32_16x16x32_bf16 v[92:95], v[132:135], v[230:233], v[92:95]
	v_mfma_f32_16x16x32_bf16 v[88:91], v[140:143], v[230:233], v[88:91]
	v_mfma_f32_16x16x32_bf16 v[76:79], v[132:135], v[238:241], v[76:79]
	v_mfma_f32_16x16x32_bf16 v[72:75], v[140:143], v[238:241], v[72:75]
	v_mfma_f32_16x16x32_bf16 v[124:127], v[136:139], v[200:203], v[124:127]
	v_mfma_f32_16x16x32_bf16 v[120:123], v[144:147], v[200:203], v[120:123]
	v_mfma_f32_16x16x32_bf16 v[108:111], v[136:139], v[214:217], v[108:111]
	v_mfma_f32_16x16x32_bf16 v[104:107], v[144:147], v[214:217], v[104:107]
	v_mfma_f32_16x16x32_bf16 v[92:95], v[136:139], v[234:237], v[92:95]
	v_mfma_f32_16x16x32_bf16 v[88:91], v[144:147], v[234:237], v[88:91]
	v_mfma_f32_16x16x32_bf16 v[76:79], v[136:139], v[242:245], v[76:79]
	v_mfma_f32_16x16x32_bf16 v[72:75], v[144:147], v[242:245], v[72:75]
	s_setprio 0
	s_setprio 1
	v_mfma_f32_16x16x32_bf16 v[116:119], v[148:151], v[188:191], v[116:119]
	v_mfma_f32_16x16x32_bf16 v[112:115], v[180:183], v[188:191], v[112:115]
	v_mfma_f32_16x16x32_bf16 v[100:103], v[148:151], v[208:211], v[100:103]
	v_mfma_f32_16x16x32_bf16 v[96:99], v[180:183], v[208:211], v[96:99]
	v_mfma_f32_16x16x32_bf16 v[84:87], v[148:151], v[230:233], v[84:87]
	v_mfma_f32_16x16x32_bf16 v[80:83], v[180:183], v[230:233], v[80:83]
	v_mfma_f32_16x16x32_bf16 v[68:71], v[148:151], v[238:241], v[68:71]
	v_mfma_f32_16x16x32_bf16 v[64:67], v[180:183], v[238:241], v[64:67]
	v_mfma_f32_16x16x32_bf16 v[116:119], v[176:179], v[200:203], v[116:119]
	v_mfma_f32_16x16x32_bf16 v[112:115], v[184:187], v[200:203], v[112:115]
	v_mfma_f32_16x16x32_bf16 v[100:103], v[176:179], v[214:217], v[100:103]
	v_mfma_f32_16x16x32_bf16 v[96:99], v[184:187], v[214:217], v[96:99]
	v_mfma_f32_16x16x32_bf16 v[84:87], v[176:179], v[234:237], v[84:87]
	v_mfma_f32_16x16x32_bf16 v[80:83], v[184:187], v[234:237], v[80:83]
	v_mfma_f32_16x16x32_bf16 v[68:71], v[176:179], v[242:245], v[68:71]
	v_mfma_f32_16x16x32_bf16 v[64:67], v[184:187], v[242:245], v[64:67]
	s_setprio 0
	s_barrier
; __device__ __forceinline__ void gst16nt(void* p, u32x4 v) { __builtin_nontemporal_store(v, (g_u32x4*)p); }
; __device__ __forceinline__ u32x4 pack8(f32x4 v0, f32x4 v1) { u32x4 w; w.x = cvt_pk_bf16(v0[0], v0[1]); w.y = cvt_pk_bf16(v0[2], v0[3]); w.z = cvt_pk_bf16(v1[0], v1[1]); w.w = cvt_pk_bf16(v1[2], v1[3]); return w; }
; #define PG8_STAGE(bufoff, gbase, voff) do { _Pragma("unroll") for (int _i = 0; _i < 2; ++_i) \
;         __builtin_amdgcn_global_load_lds((const unsigned*)((const char*)(gbase) + (voff)[_i]), (LAS unsigned*)(lds + (bufoff) + ldsw + _i * 8192), 16, 0, 0); } while (0)
;     __device__ __forceinline__ void operator()(EPI_ARGS) const {
;         const int row0 = u.om * BM + wr * 64 + fr, col0 = u.on * BM + wc * 32 + 8 * fq;
;         float rs[2][4];
;         { f32x4 pa[2][4];
; #pragma unroll
;           for (int ai = 0; ai < 2; ++ai)
; #pragma unroll
;               for (int m = 0; m < 4; ++m) pa[ai][m] = gldf4(ss + (size_t)(row0 + ai * HALF + m * 16) * 16 + fq * 4);
; #pragma unroll
;           for (int ai = 0; ai < 2; ++ai)
; #pragma unroll
;               for (int m = 0; m < 4; ++m) rs[ai][m] = rsqrtf(red4((pa[ai][m][0] + pa[ai][m][1]) + (pa[ai][m][2] + pa[ai][m][3])) * (1.0f / 1024.0f) + EPS); }
; #pragma unroll
;         for (int ai = 0; ai < 2; ++ai)
; #pragma unroll
;             for (int m = 0; m < 4; ++m) { const int row = row0 + ai * HALF + m * 16; const float r = rs[ai][m];
; #pragma unroll
;                 for (int bj = 0; bj < 2; ++bj) { f32x4 v0 = acc[ai][bj][m][0] * r, v1 = acc[ai][bj][m][1] * r;
;                     if (ACT == 1) {
; #pragma unroll
;                         for (int j = 0; j < 4; ++j) { const float x = fmaxf(v0[j], 0.f), y = fmaxf(v1[j], 0.f); v0[j] = x * x; v1[j] = y * y; } }
;                     const int c = col0 + bj * HALF;
;                     if (UMODE == 0) { if (ACT == 1) gst16nt(O + (size_t)row * ldc + c, pack8(v0, v1)); else gst16(O + (size_t)row * ldc + c, pack8(v0, v1)); }
;                     else { const int g = c >> 4, h0 = c & 15; gst16(O + ((size_t)(g * 2048 + (row >> 4)) * 256 + (row & 15) * 16 + h0), pack8(v0, v1)); } } }
;     ...
;             PG8_LDA(At, 1, 1); PG8_STAGE(PG8_SB(1, 0), b3, voffB); PG8_STAGE(PG8_SB(1, 1), b3 + hB, voffB); PG8_STAGE(PG8_SA(1, 0), a3, voffA);
;             PG8_WAIT_V(8); PG8_WAIT_L(0); PG8_BAR; PG8_MMA(1, 0, At, B0); PG8_MMA(1, 1, At, B1); PG8_BAR; PG8_SCHED;
	s_add_i32 s76, s82, s5
	v_lshl_add_u64 v[196:197], v[196:197], 0, s[38:39]
	s_mov_b32 m0, s76
	ds_read_b128 v[188:191], v198 offset:49152
	ds_read_b128 v[200:203], v198 offset:50176
	ds_read_b128 v[208:211], v198 offset:51200
	ds_read_b128 v[214:217], v198 offset:52224
	ds_read_b128 v[230:233], v198 offset:53248
	ds_read_b128 v[234:237], v198 offset:54272
	ds_read_b128 v[238:241], v198 offset:55296
	ds_read_b128 v[242:245], v198 offset:56320
	global_load_lds_dwordx4 v[196:197], off
	s_add_i32 m0, s76, 0x2000
	s_add_u32 s74, s74, 0x40080
	v_lshl_add_u64 v[196:197], v[204:205], 0, s[38:39]
	s_addc_u32 s75, s75, 0
	s_add_i32 s76, s83, s5
	global_load_lds_dwordx4 v[196:197], off
	v_lshl_add_u64 v[196:197], s[74:75], 0, v[156:157]
	s_mov_b32 m0, s76
	s_nop 0
	global_load_lds_dwordx4 v[196:197], off
	v_lshl_add_u64 v[196:197], s[74:75], 0, v[168:169]
	s_add_i32 m0, s76, 0x2000
	s_nop 0
	global_load_lds_dwordx4 v[196:197], off
	v_lshl_add_u64 v[196:197], s[72:73], 0, v[152:153]
	s_mov_b32 m0, s36
	s_nop 0
	global_load_lds_dwordx4 v[196:197], off
	v_lshl_add_u64 v[196:197], s[72:73], 0, v[154:155]
	s_mov_b32 m0, s42
	s_nop 0
	global_load_lds_dwordx4 v[196:197], off
	s_waitcnt vmcnt(8)
	s_waitcnt lgkmcnt(0)
	s_barrier
	s_setprio 1
	s_waitcnt lgkmcnt(0)
	v_mfma_f32_16x16x32_bf16 v[60:63], v[132:135], v[188:191], v[60:63]
	v_mfma_f32_16x16x32_bf16 v[56:59], v[140:143], v[188:191], v[56:59]
	v_mfma_f32_16x16x32_bf16 v[44:47], v[132:135], v[208:211], v[44:47]
	v_mfma_f32_16x16x32_bf16 v[40:43], v[140:143], v[208:211], v[40:43]
	v_mfma_f32_16x16x32_bf16 v[28:31], v[132:135], v[230:233], v[28:31]
	v_mfma_f32_16x16x32_bf16 v[24:27], v[140:143], v[230:233], v[24:27]
	v_mfma_f32_16x16x32_bf16 v[12:15], v[132:135], v[238:241], v[12:15]
	v_mfma_f32_16x16x32_bf16 v[8:11], v[140:143], v[238:241], v[8:11]
	v_mfma_f32_16x16x32_bf16 v[60:63], v[136:139], v[200:203], v[60:63]
	v_mfma_f32_16x16x32_bf16 v[56:59], v[144:147], v[200:203], v[56:59]
	v_mfma_f32_16x16x32_bf16 v[44:47], v[136:139], v[214:217], v[44:47]
	v_mfma_f32_16x16x32_bf16 v[40:43], v[144:147], v[214:217], v[40:43]
	v_mfma_f32_16x16x32_bf16 v[28:31], v[136:139], v[234:237], v[28:31]
	v_mfma_f32_16x16x32_bf16 v[24:27], v[144:147], v[234:237], v[24:27]
	v_mfma_f32_16x16x32_bf16 v[12:15], v[136:139], v[242:245], v[12:15]
	v_mfma_f32_16x16x32_bf16 v[8:11], v[144:147], v[242:245], v[8:11]
	s_setprio 0
	s_setprio 1
	v_mfma_f32_16x16x32_bf16 v[52:55], v[148:151], v[188:191], v[52:55]
	v_mfma_f32_16x16x32_bf16 v[48:51], v[180:183], v[188:191], v[48:51]
	v_mfma_f32_16x16x32_bf16 v[36:39], v[148:151], v[208:211], v[36:39]
	v_mfma_f32_16x16x32_bf16 v[32:35], v[180:183], v[208:211], v[32:35]
	v_mfma_f32_16x16x32_bf16 v[20:23], v[148:151], v[230:233], v[20:23]
	v_mfma_f32_16x16x32_bf16 v[16:19], v[180:183], v[230:233], v[16:19]
	v_mfma_f32_16x16x32_bf16 v[4:7], v[148:151], v[238:241], v[4:7]
	v_mfma_f32_16x16x32_bf16 v[0:3], v[180:183], v[238:241], v[0:3]
	v_mfma_f32_16x16x32_bf16 v[52:55], v[176:179], v[200:203], v[52:55]
	v_mfma_f32_16x16x32_bf16 v[48:51], v[184:187], v[200:203], v[48:51]
	v_mfma_f32_16x16x32_bf16 v[36:39], v[176:179], v[214:217], v[36:39]
	v_mfma_f32_16x16x32_bf16 v[32:35], v[184:187], v[214:217], v[32:35]
	v_mfma_f32_16x16x32_bf16 v[20:23], v[176:179], v[234:237], v[20:23]
	v_mfma_f32_16x16x32_bf16 v[16:19], v[184:187], v[234:237], v[16:19]
	v_mfma_f32_16x16x32_bf16 v[4:7], v[176:179], v[242:245], v[4:7]
	v_mfma_f32_16x16x32_bf16 v[0:3], v[184:187], v[242:245], v[0:3]
	s_setprio 0
	s_barrier
	s_add_i32 s81, s81, 2
	s_add_u32 s52, s52, 0x100
	s_addc_u32 s53, s53, 0
	s_cmp_gt_u32 s81, 13
	s_cbranch_scc0 .LBB0_299
.Lup_after_loop:
	s_and_b64 vcc, exec, s[16:17]
	s_cbranch_vccz .LBB0_302
	s_barrier
.LBB0_302:
	v_add_u32_e32 v250, 0x2000, v250
	global_load_dwordx4 v[132:135], v250, s[90:91]
	global_load_dwordx4 v[136:139], v250, s[90:91] offset:1024
	global_load_dwordx4 v[140:143], v250, s[90:91] offset:2048
	global_load_dwordx4 v[144:147], v250, s[90:91] offset:3072
	v_add_u32_e32 v207, 0x80000, v207
	s_waitcnt vmcnt(0)
	v_add_f32_e32 v132, v132, v133
	v_add_f32_e32 v134, v134, v135
	v_add_f32_e32 v132, v132, v134
	v_mov_b32_e32 v206, v132
	s_nop 1
	v_permlane16_swap_b32_e32 v132, v206
	v_add_f32_e32 v132, v132, v206
	v_mov_b32_e32 v206, v132
	s_nop 1
	v_permlane32_swap_b32_e32 v132, v206
	v_add_f32_e32 v132, v132, v206
	v_fmamk_f32 v132, v132, 0x3a800000, v251
	v_rsq_f32_e32 v148, v132
	v_add_f32_e32 v136, v136, v137
	v_add_f32_e32 v138, v138, v139
	v_add_f32_e32 v136, v136, v138
	v_mov_b32_e32 v206, v136
	s_nop 1
	v_permlane16_swap_b32_e32 v136, v206
	v_add_f32_e32 v136, v136, v206
	v_mov_b32_e32 v206, v136
	s_nop 1
	v_permlane32_swap_b32_e32 v136, v206
	v_add_f32_e32 v136, v136, v206
	v_fmamk_f32 v136, v136, 0x3a800000, v251
	v_rsq_f32_e32 v149, v136
	v_add_f32_e32 v140, v140, v141
	v_add_f32_e32 v142, v142, v143
	v_add_f32_e32 v140, v140, v142
	v_mov_b32_e32 v206, v140
	s_nop 1
	v_permlane16_swap_b32_e32 v140, v206
	v_add_f32_e32 v140, v140, v206
	v_mov_b32_e32 v206, v140
	s_nop 1
	v_permlane32_swap_b32_e32 v140, v206
	v_add_f32_e32 v140, v140, v206
	v_fmamk_f32 v140, v140, 0x3a800000, v251
	v_rsq_f32_e32 v150, v140
	v_add_f32_e32 v144, v144, v145
	v_add_f32_e32 v146, v146, v147
	v_add_f32_e32 v144, v144, v146
	v_mov_b32_e32 v206, v144
	s_nop 1
	v_permlane16_swap_b32_e32 v144, v206
	v_add_f32_e32 v144, v144, v206
	v_mov_b32_e32 v206, v144
	s_nop 1
	v_permlane32_swap_b32_e32 v144, v206
	v_add_f32_e32 v144, v144, v206
	v_fmamk_f32 v144, v144, 0x3a800000, v251
	v_rsq_f32_e32 v151, v144
	v_mul_f32_e32 v48, v148, v48
	v_max_f32_e32 v48, 0, v48
	v_mul_f32_e32 v48, v48, v48
	v_mul_f32_e32 v49, v148, v49
; __device__ __forceinline__ void gst16nt(void* p, u32x4 v) { __builtin_nontemporal_store(v, (g_u32x4*)p); }
; __device__ __forceinline__ u32x4 pack8(f32x4 v0, f32x4 v1) { u32x4 w; w.x = cvt_pk_bf16(v0[0], v0[1]); w.y = cvt_pk_bf16(v0[2], v0[3]); w.z = cvt_pk_bf16(v1[0], v1[1]); w.w = cvt_pk_bf16(v1[2], v1[3]); return w; }
;     __device__ __forceinline__ void operator()(EPI_ARGS) const {
;     ...
; #pragma unroll
;         for (int ai = 0; ai < 2; ++ai)
; #pragma unroll
;             for (int m = 0; m < 4; ++m) { const int row = row0 + ai * HALF + m * 16; const float r = rs[ai][m];
; #pragma unroll
;                 for (int bj = 0; bj < 2; ++bj) { f32x4 v0 = acc[ai][bj][m][0] * r, v1 = acc[ai][bj][m][1] * r;
;                     if (ACT == 1) {
; #pragma unroll
;                         for (int j = 0; j < 4; ++j) { const float x = fmaxf(v0[j], 0.f), y = fmaxf(v1[j], 0.f); v0[j] = x * x; v1[j] = y * y; } }
;                     const int c = col0 + bj * HALF;
;                     if (UMODE == 0) { if (ACT == 1) gst16nt(O + (size_t)row * ldc + c, pack8(v0, v1)); else gst16(O + (size_t)row * ldc + c, pack8(v0, v1)); }
;                     else { const int g = c >> 4, h0 = c & 15; gst16(O + ((size_t)(g * 2048 + (row >> 4)) * 256 + (row & 15) * 16 + h0), pack8(v0, v1)); } } }
	v_max_f32_e32 v49, 0, v49
	v_mul_f32_e32 v49, v49, v49
	v_mul_f32_e32 v50, v148, v50
	v_max_f32_e32 v50, 0, v50
	v_mul_f32_e32 v50, v50, v50
	v_mul_f32_e32 v51, v148, v51
	v_max_f32_e32 v51, 0, v51
	v_mul_f32_e32 v51, v51, v51
	v_mul_f32_e32 v52, v148, v52
	v_max_f32_e32 v52, 0, v52
	v_mul_f32_e32 v52, v52, v52
	v_mul_f32_e32 v53, v148, v53
	v_max_f32_e32 v53, 0, v53
	v_mul_f32_e32 v53, v53, v53
	v_mul_f32_e32 v54, v148, v54
	v_max_f32_e32 v54, 0, v54
	v_mul_f32_e32 v54, v54, v54
	v_mul_f32_e32 v55, v148, v55
	v_max_f32_e32 v55, 0, v55
	v_mul_f32_e32 v55, v55, v55
	v_mul_f32_e32 v56, v148, v56
	v_max_f32_e32 v56, 0, v56
	v_mul_f32_e32 v56, v56, v56
	v_mul_f32_e32 v57, v148, v57
	v_max_f32_e32 v57, 0, v57
	v_mul_f32_e32 v57, v57, v57
	v_mul_f32_e32 v58, v148, v58
	v_max_f32_e32 v58, 0, v58
	v_mul_f32_e32 v58, v58, v58
	v_mul_f32_e32 v59, v148, v59
	v_max_f32_e32 v59, 0, v59
	v_mul_f32_e32 v59, v59, v59
	v_mul_f32_e32 v60, v148, v60
	v_max_f32_e32 v60, 0, v60
	v_mul_f32_e32 v60, v60, v60
	v_mul_f32_e32 v61, v148, v61
	v_max_f32_e32 v61, 0, v61
	v_mul_f32_e32 v61, v61, v61
	v_mul_f32_e32 v62, v148, v62
	v_max_f32_e32 v62, 0, v62
	v_mul_f32_e32 v62, v62, v62
	v_mul_f32_e32 v63, v148, v63
	v_max_f32_e32 v63, 0, v63
	v_mul_f32_e32 v63, v63, v63
	v_cvt_pk_bf16_f32 v60, v60, v61
	v_cvt_pk_bf16_f32 v61, v62, v63
	v_cvt_pk_bf16_f32 v62, v56, v57
	v_cvt_pk_bf16_f32 v63, v58, v59
	global_store_dwordx4 v207, v[60:63], s[24:25] nt
	v_cvt_pk_bf16_f32 v52, v52, v53
	v_cvt_pk_bf16_f32 v53, v54, v55
	v_cvt_pk_bf16_f32 v54, v48, v49
	v_cvt_pk_bf16_f32 v55, v50, v51
	global_store_dwordx4 v207, v[52:55], s[24:25] offset:256 nt
	v_add_u32_e32 v207, 0x20000, v207
	v_mul_f32_e32 v32, v149, v32
	v_max_f32_e32 v32, 0, v32
	v_mul_f32_e32 v32, v32, v32
	v_mul_f32_e32 v33, v149, v33
	v_max_f32_e32 v33, 0, v33
	v_mul_f32_e32 v33, v33, v33
	v_mul_f32_e32 v34, v149, v34
	v_max_f32_e32 v34, 0, v34
	v_mul_f32_e32 v34, v34, v34
	v_mul_f32_e32 v35, v149, v35
	v_max_f32_e32 v35, 0, v35
	v_mul_f32_e32 v35, v35, v35
	v_mul_f32_e32 v36, v149, v36
	v_max_f32_e32 v36, 0, v36
	v_mul_f32_e32 v36, v36, v36
	v_mul_f32_e32 v37, v149, v37
	v_max_f32_e32 v37, 0, v37
	v_mul_f32_e32 v37, v37, v37
	v_mul_f32_e32 v38, v149, v38
	v_max_f32_e32 v38, 0, v38
	v_mul_f32_e32 v38, v38, v38
	v_mul_f32_e32 v39, v149, v39
	v_max_f32_e32 v39, 0, v39
	v_mul_f32_e32 v39, v39, v39
	v_mul_f32_e32 v40, v149, v40
	v_max_f32_e32 v40, 0, v40
	v_mul_f32_e32 v40, v40, v40
	v_mul_f32_e32 v41, v149, v41
	v_max_f32_e32 v41, 0, v41
	v_mul_f32_e32 v41, v41, v41
	v_mul_f32_e32 v42, v149, v42
	v_max_f32_e32 v42, 0, v42
	v_mul_f32_e32 v42, v42, v42
	v_mul_f32_e32 v43, v149, v43
	v_max_f32_e32 v43, 0, v43
	v_mul_f32_e32 v43, v43, v43
	v_mul_f32_e32 v44, v149, v44
	v_max_f32_e32 v44, 0, v44
	v_mul_f32_e32 v44, v44, v44
	v_mul_f32_e32 v45, v149, v45
	v_max_f32_e32 v45, 0, v45
	v_mul_f32_e32 v45, v45, v45
	v_mul_f32_e32 v46, v149, v46
	v_max_f32_e32 v46, 0, v46
	v_mul_f32_e32 v46, v46, v46
	v_mul_f32_e32 v47, v149, v47
	v_max_f32_e32 v47, 0, v47
	v_mul_f32_e32 v47, v47, v47
	v_cvt_pk_bf16_f32 v44, v44, v45
	v_cvt_pk_bf16_f32 v45, v46, v47
	v_cvt_pk_bf16_f32 v46, v40, v41
	v_cvt_pk_bf16_f32 v47, v42, v43
	global_store_dwordx4 v207, v[44:47], s[24:25] nt
	v_cvt_pk_bf16_f32 v36, v36, v37
	v_cvt_pk_bf16_f32 v37, v38, v39
	v_cvt_pk_bf16_f32 v38, v32, v33
	v_cvt_pk_bf16_f32 v39, v34, v35
	global_store_dwordx4 v207, v[36:39], s[24:25] offset:256 nt
	v_add_u32_e32 v207, 0x20000, v207
	v_mul_f32_e32 v16, v150, v16
	v_max_f32_e32 v16, 0, v16
	v_mul_f32_e32 v16, v16, v16
	v_mul_f32_e32 v17, v150, v17
	v_max_f32_e32 v17, 0, v17
	v_mul_f32_e32 v17, v17, v17
	v_mul_f32_e32 v18, v150, v18
	v_max_f32_e32 v18, 0, v18
	v_mul_f32_e32 v18, v18, v18
	v_mul_f32_e32 v19, v150, v19
	v_max_f32_e32 v19, 0, v19
	v_mul_f32_e32 v19, v19, v19
	v_mul_f32_e32 v20, v150, v20
	v_max_f32_e32 v20, 0, v20
	v_mul_f32_e32 v20, v20, v20
	v_mul_f32_e32 v21, v150, v21
	v_max_f32_e32 v21, 0, v21
	v_mul_f32_e32 v21, v21, v21
	v_mul_f32_e32 v22, v150, v22
	v_max_f32_e32 v22, 0, v22
	v_mul_f32_e32 v22, v22, v22
	v_mul_f32_e32 v23, v150, v23
	v_max_f32_e32 v23, 0, v23
	v_mul_f32_e32 v23, v23, v23
	v_mul_f32_e32 v24, v150, v24
	v_max_f32_e32 v24, 0, v24
	v_mul_f32_e32 v24, v24, v24
	v_mul_f32_e32 v25, v150, v25
	v_max_f32_e32 v25, 0, v25
	v_mul_f32_e32 v25, v25, v25
	v_mul_f32_e32 v26, v150, v26
	v_max_f32_e32 v26, 0, v26
	v_mul_f32_e32 v26, v26, v26
	v_mul_f32_e32 v27, v150, v27
	v_max_f32_e32 v27, 0, v27
	v_mul_f32_e32 v27, v27, v27
	v_mul_f32_e32 v28, v150, v28
	v_max_f32_e32 v28, 0, v28
	v_mul_f32_e32 v28, v28, v28
	v_mul_f32_e32 v29, v150, v29
	v_max_f32_e32 v29, 0, v29
	v_mul_f32_e32 v29, v29, v29
	v_mul_f32_e32 v30, v150, v30
	v_max_f32_e32 v30, 0, v30
	v_mul_f32_e32 v30, v30, v30
	v_mul_f32_e32 v31, v150, v31
	v_max_f32_e32 v31, 0, v31
	v_mul_f32_e32 v31, v31, v31
	v_cvt_pk_bf16_f32 v28, v28, v29
	v_cvt_pk_bf16_f32 v29, v30, v31
	v_cvt_pk_bf16_f32 v30, v24, v25
	v_cvt_pk_bf16_f32 v31, v26, v27
	global_store_dwordx4 v207, v[28:31], s[24:25] nt
	v_cvt_pk_bf16_f32 v20, v20, v21
	v_cvt_pk_bf16_f32 v21, v22, v23
	v_cvt_pk_bf16_f32 v22, v16, v17
	v_cvt_pk_bf16_f32 v23, v18, v19
	global_store_dwordx4 v207, v[20:23], s[24:25] offset:256 nt
	v_add_u32_e32 v207, 0x20000, v207
	v_mul_f32_e32 v0, v151, v0
	v_max_f32_e32 v0, 0, v0
	v_mul_f32_e32 v0, v0, v0
	v_mul_f32_e32 v1, v151, v1
	v_max_f32_e32 v1, 0, v1
	v_mul_f32_e32 v1, v1, v1
	v_mul_f32_e32 v2, v151, v2
	v_max_f32_e32 v2, 0, v2
	v_mul_f32_e32 v2, v2, v2
	v_mul_f32_e32 v3, v151, v3
	v_max_f32_e32 v3, 0, v3
	v_mul_f32_e32 v3, v3, v3
	v_mul_f32_e32 v4, v151, v4
	v_max_f32_e32 v4, 0, v4
	v_mul_f32_e32 v4, v4, v4
	v_mul_f32_e32 v5, v151, v5
	v_max_f32_e32 v5, 0, v5
	v_mul_f32_e32 v5, v5, v5
	v_mul_f32_e32 v6, v151, v6
	v_max_f32_e32 v6, 0, v6
	v_mul_f32_e32 v6, v6, v6
	v_mul_f32_e32 v7, v151, v7
	v_max_f32_e32 v7, 0, v7
	v_mul_f32_e32 v7, v7, v7
	v_mul_f32_e32 v8, v151, v8
	v_max_f32_e32 v8, 0, v8
	v_mul_f32_e32 v8, v8, v8
	v_mul_f32_e32 v9, v151, v9
	v_max_f32_e32 v9, 0, v9
	v_mul_f32_e32 v9, v9, v9
	v_mul_f32_e32 v10, v151, v10
	v_max_f32_e32 v10, 0, v10
	v_mul_f32_e32 v10, v10, v10
	v_mul_f32_e32 v11, v151, v11
	v_max_f32_e32 v11, 0, v11
	v_mul_f32_e32 v11, v11, v11
	v_mul_f32_e32 v12, v151, v12
	v_max_f32_e32 v12, 0, v12
	v_mul_f32_e32 v12, v12, v12
	v_mul_f32_e32 v13, v151, v13
	v_max_f32_e32 v13, 0, v13
	v_mul_f32_e32 v13, v13, v13
	v_mul_f32_e32 v14, v151, v14
	v_max_f32_e32 v14, 0, v14
	v_mul_f32_e32 v14, v14, v14
	v_mul_f32_e32 v15, v151, v15
	v_max_f32_e32 v15, 0, v15
	v_mul_f32_e32 v15, v15, v15
	v_cvt_pk_bf16_f32 v12, v12, v13
	v_cvt_pk_bf16_f32 v13, v14, v15
	v_cvt_pk_bf16_f32 v14, v8, v9
	v_cvt_pk_bf16_f32 v15, v10, v11
	global_store_dwordx4 v207, v[12:15], s[24:25] nt
	v_cvt_pk_bf16_f32 v4, v4, v5
	v_cvt_pk_bf16_f32 v5, v6, v7
	v_cvt_pk_bf16_f32 v6, v0, v1
	v_cvt_pk_bf16_f32 v7, v2, v3
	global_store_dwordx4 v207, v[4:7], s[24:25] offset:256 nt
	v_add_u32_e32 v207, 0x20000, v207
	s_mov_b64 s[2:3], -1
	s_andn2_b64 vcc, exec, s[40:41]
	s_cbranch_vccnz .LBB0_291
; #define PG8_STAGE(bufoff, gbase, voff) do { _Pragma("unroll") for (int _i = 0; _i < 2; ++_i) \
;         __builtin_amdgcn_global_load_lds((const unsigned*)((const char*)(gbase) + (voff)[_i]), (LAS unsigned*)(lds + (bufoff) + ldsw + _i * 8192), 16, 0, 0); } while (0)
; #define PG8_LDA(dst, b, h) do { _Pragma("unroll") for (int m = 0; m < 4; ++m) _Pragma("unroll") for (int k = 0; k < 2; ++k) dst[m][k] = *(const LAS bf16x8*)(lds + PG8_SA(b, h) + aoff + m * 2048 + k * 1024); } while (0)
; #define PG8_LDB(dst, b, h) do { _Pragma("unroll") for (int n = 0; n < 2; ++n) _Pragma("unroll") for (int k = 0; k < 2; ++k) dst[n][k] = *(const LAS bf16x8*)(lds + PG8_SB(b, h) + boff + n * 2048 + k * 1024); } while (0)
; #define PG8_MMA(ai, bj, At, Bt) do { __builtin_amdgcn_s_setprio(1); _Pragma("unroll") for (int m = 0; m < 4; ++m) _Pragma("unroll") for (int n = 0; n < 2; ++n) _Pragma("unroll") for (int k = 0; k < 2; ++k) \
;         acc[ai][bj][m][n] = __builtin_amdgcn_mfma_f32_16x16x32_bf16(Bt[n][k], At[m][k], acc[ai][bj][m][n], 0, 0, 0); __builtin_amdgcn_s_setprio(0); } while (0)
; #define PG8_WAIT_V(n) asm volatile("s_waitcnt vmcnt(" #n ")" ::: "memory")
; #define PG8_WAIT_L(n) asm volatile("s_waitcnt lgkmcnt(" #n ")" ::: "memory")
; #define PG8_BAR __builtin_amdgcn_s_barrier()
;     ...
;             PG8_LDB(B0, 0, 0); PG8_LDB(B1, 0, 1); PG8_SCHED; PG8_LDA(At, 0, 0); PG8_STAGE(PG8_SA(1, 1), a1 + hA, voffA);
;             PG8_WAIT_V(8); PG8_WAIT_L(0); PG8_BAR; PG8_MMA(0, 0, At, B0); PG8_MMA(0, 1, At, B1); PG8_BAR; PG8_SCHED;
;             PG8_LDA(At, 0, 1); PG8_STAGE(PG8_SB(0, 0), b2, voffB); PG8_STAGE(PG8_SB(0, 1), b2 + hB, voffB); PG8_STAGE(PG8_SA(0, 0), a2, voffA);
;             PG8_WAIT_V(8); PG8_WAIT_L(0); PG8_BAR; PG8_MMA(1, 0, At, B0); PG8_MMA(1, 1, At, B1); PG8_BAR; PG8_SCHED;
;             PG8_LDB(B0, 1, 0); PG8_LDB(B1, 1, 1); PG8_SCHED; PG8_LDA(At, 1, 0); PG8_STAGE(PG8_SA(0, 1), a2 + hA, voffA);
;             PG8_WAIT_V(8); PG8_WAIT_L(0); PG8_BAR; PG8_MMA(0, 0, At, B0); PG8_MMA(0, 1, At, B1); PG8_BAR; PG8_SCHED;
;             PG8_LDA(At, 1, 1); PG8_STAGE(PG8_SB(1, 0), b3, voffB); PG8_STAGE(PG8_SB(1, 1), b3 + hB, voffB); PG8_STAGE(PG8_SA(1, 0), a3, voffA);
;             PG8_WAIT_V(8); PG8_WAIT_L(0); PG8_BAR; PG8_MMA(1, 0, At, B0); PG8_MMA(1, 1, At, B1); PG8_BAR; PG8_SCHED;
;     ...
;         if constexpr (ALIGN_EPI) { if (wr == 1) PG8_BAR; }
	s_andn2_b64 vcc, exec, s[14:15]
	s_cbranch_vccnz .LBB0_290
	s_barrier
	s_branch .LBB0_290
.Lup_last:
	s_add_i32 s82, 0, 0x18000
	s_add_i32 s83, 0, 0x1c000
	v_add_u32_e32 v144, s82, v193
	v_add_u32_e32 v184, s83, v193
	ds_read_b128 v[132:135], v144
	ds_read_b128 v[136:139], v144 offset:1024
	ds_read_b128 v[140:143], v144 offset:2048
	ds_read_b128 v[144:147], v144 offset:3072
	ds_read_b128 v[148:151], v184
	ds_read_b128 v[176:179], v184 offset:1024
	ds_read_b128 v[180:183], v184 offset:2048
	ds_read_b128 v[184:187], v184 offset:3072
	s_add_u32 s76, s76, 0x40000
	s_addc_u32 s77, s77, 0
	s_mov_b32 m0, s8
	v_lshl_add_u64 v[206:207], s[76:77], 0, v[152:153]
	ds_read_b128 v[188:191], v198 offset:32768
	ds_read_b128 v[200:203], v198 offset:33792
	ds_read_b128 v[208:211], v198 offset:34816
	ds_read_b128 v[214:217], v198 offset:35840
	ds_read_b128 v[230:233], v198 offset:36864
	ds_read_b128 v[234:237], v198 offset:37888
	ds_read_b128 v[238:241], v198 offset:38912
	ds_read_b128 v[242:245], v198 offset:39936
	global_load_lds_dwordx4 v[206:207], off
	v_lshl_add_u64 v[206:207], s[76:77], 0, v[154:155]
	s_mov_b32 m0, s9
	s_nop 0
	global_load_lds_dwordx4 v[206:207], off
	v_bfe_u32 v251, v164, 4, 2
	v_lshlrev_b32_e32 v251, 4, v251
	v_lshl_add_u32 v251, v165, 6, v251
	s_lshl_b32 s98, s2, 14
	v_add_u32_e32 v250, s98, v251
	global_load_dwordx4 v[246:249], v250, s[90:91]
	global_load_dwordx4 v[128:131], v250, s[90:91] offset:1024
	s_waitcnt vmcnt(10)
	s_waitcnt lgkmcnt(0)
	s_barrier
	s_setprio 1
	s_waitcnt lgkmcnt(0)
	v_mfma_f32_16x16x32_bf16 v[124:127], v[132:135], v[188:191], v[124:127]
	v_mfma_f32_16x16x32_bf16 v[120:123], v[140:143], v[188:191], v[120:123]
	v_mfma_f32_16x16x32_bf16 v[108:111], v[132:135], v[208:211], v[108:111]
	v_mfma_f32_16x16x32_bf16 v[104:107], v[140:143], v[208:211], v[104:107]
	v_mfma_f32_16x16x32_bf16 v[92:95], v[132:135], v[230:233], v[92:95]
	v_mfma_f32_16x16x32_bf16 v[88:91], v[140:143], v[230:233], v[88:91]
	v_mfma_f32_16x16x32_bf16 v[76:79], v[132:135], v[238:241], v[76:79]
	v_mfma_f32_16x16x32_bf16 v[72:75], v[140:143], v[238:241], v[72:75]
	v_mfma_f32_16x16x32_bf16 v[124:127], v[136:139], v[200:203], v[124:127]
	v_mfma_f32_16x16x32_bf16 v[120:123], v[144:147], v[200:203], v[120:123]
	v_mfma_f32_16x16x32_bf16 v[108:111], v[136:139], v[214:217], v[108:111]
	v_mfma_f32_16x16x32_bf16 v[104:107], v[144:147], v[214:217], v[104:107]
	v_mfma_f32_16x16x32_bf16 v[92:95], v[136:139], v[234:237], v[92:95]
	v_mfma_f32_16x16x32_bf16 v[88:91], v[144:147], v[234:237], v[88:91]
	v_mfma_f32_16x16x32_bf16 v[76:79], v[136:139], v[242:245], v[76:79]
	v_mfma_f32_16x16x32_bf16 v[72:75], v[144:147], v[242:245], v[72:75]
	s_setprio 0
	s_setprio 1
	v_mfma_f32_16x16x32_bf16 v[116:119], v[148:151], v[188:191], v[116:119]
	v_mfma_f32_16x16x32_bf16 v[112:115], v[180:183], v[188:191], v[112:115]
	v_mfma_f32_16x16x32_bf16 v[100:103], v[148:151], v[208:211], v[100:103]
	v_mfma_f32_16x16x32_bf16 v[96:99], v[180:183], v[208:211], v[96:99]
	v_mfma_f32_16x16x32_bf16 v[84:87], v[148:151], v[230:233], v[84:87]
	v_mfma_f32_16x16x32_bf16 v[80:83], v[180:183], v[230:233], v[80:83]
	v_mfma_f32_16x16x32_bf16 v[68:71], v[148:151], v[238:241], v[68:71]
	v_mfma_f32_16x16x32_bf16 v[64:67], v[180:183], v[238:241], v[64:67]
	v_mfma_f32_16x16x32_bf16 v[116:119], v[176:179], v[200:203], v[116:119]
	v_mfma_f32_16x16x32_bf16 v[112:115], v[184:187], v[200:203], v[112:115]
	v_mfma_f32_16x16x32_bf16 v[100:103], v[176:179], v[214:217], v[100:103]
	v_mfma_f32_16x16x32_bf16 v[96:99], v[184:187], v[214:217], v[96:99]
	v_mfma_f32_16x16x32_bf16 v[84:87], v[176:179], v[234:237], v[84:87]
	v_mfma_f32_16x16x32_bf16 v[80:83], v[184:187], v[234:237], v[80:83]
	v_mfma_f32_16x16x32_bf16 v[68:71], v[176:179], v[242:245], v[68:71]
	v_mfma_f32_16x16x32_bf16 v[64:67], v[184:187], v[242:245], v[64:67]
	s_setprio 0
	s_barrier
	s_add_i32 s76, s82, s5
	v_lshl_add_u64 v[196:197], v[196:197], 0, s[38:39]
	s_mov_b32 m0, s76
	ds_read_b128 v[188:191], v198 offset:49152
	ds_read_b128 v[200:203], v198 offset:50176
	ds_read_b128 v[208:211], v198 offset:51200
	ds_read_b128 v[214:217], v198 offset:52224
	ds_read_b128 v[230:233], v198 offset:53248
	ds_read_b128 v[234:237], v198 offset:54272
	ds_read_b128 v[238:241], v198 offset:55296
	ds_read_b128 v[242:245], v198 offset:56320
	global_load_lds_dwordx4 v[196:197], off
	s_add_i32 m0, s76, 0x2000
	s_add_u32 s74, s74, 0x40080
	v_lshl_add_u64 v[196:197], v[204:205], 0, s[38:39]
	s_addc_u32 s75, s75, 0
	s_add_i32 s76, s83, s5
	global_load_lds_dwordx4 v[196:197], off
	v_lshl_add_u64 v[196:197], s[74:75], 0, v[156:157]
	s_mov_b32 m0, s76
	s_nop 0
	global_load_lds_dwordx4 v[196:197], off
	v_lshl_add_u64 v[196:197], s[74:75], 0, v[168:169]
	s_add_i32 m0, s76, 0x2000
	s_nop 0
	global_load_lds_dwordx4 v[196:197], off
	v_lshl_add_u64 v[196:197], s[72:73], 0, v[152:153]
	s_mov_b32 m0, s36
	s_nop 0
	global_load_lds_dwordx4 v[196:197], off
	v_lshl_add_u64 v[196:197], s[72:73], 0, v[154:155]
	s_mov_b32 m0, s42
	s_nop 0
	global_load_lds_dwordx4 v[196:197], off
	s_waitcnt vmcnt(6)
; __device__ __forceinline__ void gst16nt(void* p, u32x4 v) { __builtin_nontemporal_store(v, (g_u32x4*)p); }
; __device__ __forceinline__ u32x4 pack8(f32x4 v0, f32x4 v1) { u32x4 w; w.x = cvt_pk_bf16(v0[0], v0[1]); w.y = cvt_pk_bf16(v0[2], v0[3]); w.z = cvt_pk_bf16(v1[0], v1[1]); w.w = cvt_pk_bf16(v1[2], v1[3]); return w; }
;     __device__ __forceinline__ void operator()(EPI_ARGS) const {
;         const int row0 = u.om * BM + wr * 64 + fr, col0 = u.on * BM + wc * 32 + 8 * fq;
;         float rs[2][4];
;         { f32x4 pa[2][4];
; #pragma unroll
;           for (int ai = 0; ai < 2; ++ai)
; #pragma unroll
;               for (int m = 0; m < 4; ++m) pa[ai][m] = gldf4(ss + (size_t)(row0 + ai * HALF + m * 16) * 16 + fq * 4);
; #pragma unroll
;           for (int ai = 0; ai < 2; ++ai)
; #pragma unroll
;               for (int m = 0; m < 4; ++m) rs[ai][m] = rsqrtf(red4((pa[ai][m][0] + pa[ai][m][1]) + (pa[ai][m][2] + pa[ai][m][3])) * (1.0f / 1024.0f) + EPS); }
; #pragma unroll
;         for (int ai = 0; ai < 2; ++ai)
; #pragma unroll
;             for (int m = 0; m < 4; ++m) { const int row = row0 + ai * HALF + m * 16; const float r = rs[ai][m];
; #pragma unroll
;                 for (int bj = 0; bj < 2; ++bj) { f32x4 v0 = acc[ai][bj][m][0] * r, v1 = acc[ai][bj][m][1] * r;
;                     if (ACT == 1) {
; #pragma unroll
;                         for (int j = 0; j < 4; ++j) { const float x = fmaxf(v0[j], 0.f), y = fmaxf(v1[j], 0.f); v0[j] = x * x; v1[j] = y * y; } }
;                     const int c = col0 + bj * HALF;
;                     if (UMODE == 0) { if (ACT == 1) gst16nt(O + (size_t)row * ldc + c, pack8(v0, v1)); else gst16(O + (size_t)row * ldc + c, pack8(v0, v1)); }
;                     else { const int g = c >> 4, h0 = c & 15; gst16(O + ((size_t)(g * 2048 + (row >> 4)) * 256 + (row & 15) * 16 + h0), pack8(v0, v1)); } } }
	v_mov_b32_e32 v251, 0x358637bd
	v_add_f32_e32 v246, v246, v247
	v_add_f32_e32 v248, v248, v249
	v_add_f32_e32 v246, v246, v248
	v_mov_b32_e32 v206, v246
	s_nop 1
	v_permlane16_swap_b32_e32 v246, v206
	v_add_f32_e32 v246, v246, v206
	v_mov_b32_e32 v206, v246
	s_nop 1
	v_permlane32_swap_b32_e32 v246, v206
	v_add_f32_e32 v246, v246, v206
	v_fmamk_f32 v246, v246, 0x3a800000, v251
	v_rsq_f32_e32 v192, v246
	v_add_f32_e32 v128, v128, v129
	v_add_f32_e32 v130, v130, v131
	v_add_f32_e32 v128, v128, v130
	v_mov_b32_e32 v206, v128
	s_nop 1
	v_permlane16_swap_b32_e32 v128, v206
	v_add_f32_e32 v128, v128, v206
	v_mov_b32_e32 v206, v128
	s_nop 1
	v_permlane32_swap_b32_e32 v128, v206
	v_add_f32_e32 v128, v128, v206
	v_fmamk_f32 v128, v128, 0x3a800000, v251
	v_rsq_f32_e32 v194, v128
	global_load_dwordx4 v[246:249], v250, s[90:91] offset:2048
	global_load_dwordx4 v[128:131], v250, s[90:91] offset:3072
	v_lshlrev_b32_e32 v207, 13, v165
	v_lshl_add_u32 v207, v195, 1, v207
	s_lshl_b32 s98, s2, 21
	s_lshl_b32 s99, s51, 9
	s_add_i32 s98, s98, s99
	v_add_u32_e32 v207, s98, v207
	v_mul_f32_e32 v112, v192, v112
	v_max_f32_e32 v112, 0, v112
	v_mul_f32_e32 v112, v112, v112
	v_mul_f32_e32 v113, v192, v113
	v_max_f32_e32 v113, 0, v113
	v_mul_f32_e32 v113, v113, v113
	v_mul_f32_e32 v114, v192, v114
	v_max_f32_e32 v114, 0, v114
	v_mul_f32_e32 v114, v114, v114
	v_mul_f32_e32 v115, v192, v115
	v_max_f32_e32 v115, 0, v115
	v_mul_f32_e32 v115, v115, v115
	v_mul_f32_e32 v116, v192, v116
	v_max_f32_e32 v116, 0, v116
	v_mul_f32_e32 v116, v116, v116
	v_mul_f32_e32 v117, v192, v117
	v_max_f32_e32 v117, 0, v117
	v_mul_f32_e32 v117, v117, v117
	v_mul_f32_e32 v118, v192, v118
	v_max_f32_e32 v118, 0, v118
	v_mul_f32_e32 v118, v118, v118
	v_mul_f32_e32 v119, v192, v119
	v_max_f32_e32 v119, 0, v119
	v_mul_f32_e32 v119, v119, v119
	v_mul_f32_e32 v120, v192, v120
	v_max_f32_e32 v120, 0, v120
	v_mul_f32_e32 v120, v120, v120
	v_mul_f32_e32 v121, v192, v121
	v_max_f32_e32 v121, 0, v121
	v_mul_f32_e32 v121, v121, v121
	v_mul_f32_e32 v122, v192, v122
	v_max_f32_e32 v122, 0, v122
	v_mul_f32_e32 v122, v122, v122
	v_mul_f32_e32 v123, v192, v123
	v_max_f32_e32 v123, 0, v123
	v_mul_f32_e32 v123, v123, v123
	v_mul_f32_e32 v124, v192, v124
	v_max_f32_e32 v124, 0, v124
	v_mul_f32_e32 v124, v124, v124
	v_mul_f32_e32 v125, v192, v125
	v_max_f32_e32 v125, 0, v125
	v_mul_f32_e32 v125, v125, v125
	v_mul_f32_e32 v126, v192, v126
	v_max_f32_e32 v126, 0, v126
	v_mul_f32_e32 v126, v126, v126
	v_mul_f32_e32 v127, v192, v127
	v_max_f32_e32 v127, 0, v127
	v_mul_f32_e32 v127, v127, v127
	v_cvt_pk_bf16_f32 v124, v124, v125
	v_cvt_pk_bf16_f32 v125, v126, v127
	v_cvt_pk_bf16_f32 v126, v120, v121
	v_cvt_pk_bf16_f32 v127, v122, v123
	global_store_dwordx4 v207, v[124:127], s[24:25] nt
	v_cvt_pk_bf16_f32 v116, v116, v117
	v_cvt_pk_bf16_f32 v117, v118, v119
	v_cvt_pk_bf16_f32 v118, v112, v113
	v_cvt_pk_bf16_f32 v119, v114, v115
	global_store_dwordx4 v207, v[116:119], s[24:25] offset:256 nt
	v_add_u32_e32 v207, 0x20000, v207
	v_mul_f32_e32 v96, v194, v96
	v_max_f32_e32 v96, 0, v96
	v_mul_f32_e32 v96, v96, v96
	v_mul_f32_e32 v97, v194, v97
	v_max_f32_e32 v97, 0, v97
	v_mul_f32_e32 v97, v97, v97
	v_mul_f32_e32 v98, v194, v98
	v_max_f32_e32 v98, 0, v98
	v_mul_f32_e32 v98, v98, v98
	v_mul_f32_e32 v99, v194, v99
	v_max_f32_e32 v99, 0, v99
	v_mul_f32_e32 v99, v99, v99
	v_mul_f32_e32 v100, v194, v100
	v_max_f32_e32 v100, 0, v100
	v_mul_f32_e32 v100, v100, v100
	v_mul_f32_e32 v101, v194, v101
	v_max_f32_e32 v101, 0, v101
	v_mul_f32_e32 v101, v101, v101
	v_mul_f32_e32 v102, v194, v102
	v_max_f32_e32 v102, 0, v102
	v_mul_f32_e32 v102, v102, v102
	v_mul_f32_e32 v103, v194, v103
	v_max_f32_e32 v103, 0, v103
	v_mul_f32_e32 v103, v103, v103
	v_mul_f32_e32 v104, v194, v104
	v_max_f32_e32 v104, 0, v104
	v_mul_f32_e32 v104, v104, v104
	v_mul_f32_e32 v105, v194, v105
	v_max_f32_e32 v105, 0, v105
	v_mul_f32_e32 v105, v105, v105
	v_mul_f32_e32 v106, v194, v106
	v_max_f32_e32 v106, 0, v106
	v_mul_f32_e32 v106, v106, v106
	v_mul_f32_e32 v107, v194, v107
	v_max_f32_e32 v107, 0, v107
	v_mul_f32_e32 v107, v107, v107
	v_mul_f32_e32 v108, v194, v108
	v_max_f32_e32 v108, 0, v108
	v_mul_f32_e32 v108, v108, v108
	v_mul_f32_e32 v109, v194, v109
	v_max_f32_e32 v109, 0, v109
	v_mul_f32_e32 v109, v109, v109
	v_mul_f32_e32 v110, v194, v110
	v_max_f32_e32 v110, 0, v110
	v_mul_f32_e32 v110, v110, v110
	v_mul_f32_e32 v111, v194, v111
	v_max_f32_e32 v111, 0, v111
	v_mul_f32_e32 v111, v111, v111
	v_cvt_pk_bf16_f32 v108, v108, v109
	v_cvt_pk_bf16_f32 v109, v110, v111
	v_cvt_pk_bf16_f32 v110, v104, v105
	v_cvt_pk_bf16_f32 v111, v106, v107
	global_store_dwordx4 v207, v[108:111], s[24:25] nt
	v_cvt_pk_bf16_f32 v100, v100, v101
	v_cvt_pk_bf16_f32 v101, v102, v103
	v_cvt_pk_bf16_f32 v102, v96, v97
	v_cvt_pk_bf16_f32 v103, v98, v99
	global_store_dwordx4 v207, v[100:103], s[24:25] offset:256 nt
	v_add_u32_e32 v207, 0x20000, v207
	s_waitcnt lgkmcnt(0)
	s_barrier
; __device__ __forceinline__ void gst16nt(void* p, u32x4 v) { __builtin_nontemporal_store(v, (g_u32x4*)p); }
; __device__ __forceinline__ u32x4 pack8(f32x4 v0, f32x4 v1) { u32x4 w; w.x = cvt_pk_bf16(v0[0], v0[1]); w.y = cvt_pk_bf16(v0[2], v0[3]); w.z = cvt_pk_bf16(v1[0], v1[1]); w.w = cvt_pk_bf16(v1[2], v1[3]); return w; }
; #define PG8_STAGE(bufoff, gbase, voff) do { _Pragma("unroll") for (int _i = 0; _i < 2; ++_i) \
;         __builtin_amdgcn_global_load_lds((const unsigned*)((const char*)(gbase) + (voff)[_i]), (LAS unsigned*)(lds + (bufoff) + ldsw + _i * 8192), 16, 0, 0); } while (0)
; #define PG8_LDA(dst, b, h) do { _Pragma("unroll") for (int m = 0; m < 4; ++m) _Pragma("unroll") for (int k = 0; k < 2; ++k) dst[m][k] = *(const LAS bf16x8*)(lds + PG8_SA(b, h) + aoff + m * 2048 + k * 1024); } while (0)
;     __device__ __forceinline__ void operator()(EPI_ARGS) const {
;     ...
;               for (int m = 0; m < 4; ++m) pa[ai][m] = gldf4(ss + (size_t)(row0 + ai * HALF + m * 16) * 16 + fq * 4);
; #pragma unroll
;           for (int ai = 0; ai < 2; ++ai)
; #pragma unroll
;               for (int m = 0; m < 4; ++m) rs[ai][m] = rsqrtf(red4((pa[ai][m][0] + pa[ai][m][1]) + (pa[ai][m][2] + pa[ai][m][3])) * (1.0f / 1024.0f) + EPS); }
; #pragma unroll
;         for (int ai = 0; ai < 2; ++ai)
; #pragma unroll
;             for (int m = 0; m < 4; ++m) { const int row = row0 + ai * HALF + m * 16; const float r = rs[ai][m];
; #pragma unroll
;                 for (int bj = 0; bj < 2; ++bj) { f32x4 v0 = acc[ai][bj][m][0] * r, v1 = acc[ai][bj][m][1] * r;
;                     if (ACT == 1) {
; #pragma unroll
;                         for (int j = 0; j < 4; ++j) { const float x = fmaxf(v0[j], 0.f), y = fmaxf(v1[j], 0.f); v0[j] = x * x; v1[j] = y * y; } }
;                     const int c = col0 + bj * HALF;
;                     if (UMODE == 0) { if (ACT == 1) gst16nt(O + (size_t)row * ldc + c, pack8(v0, v1)); else gst16(O + (size_t)row * ldc + c, pack8(v0, v1)); }
;                     else { const int g = c >> 4, h0 = c & 15; gst16(O + ((size_t)(g * 2048 + (row >> 4)) * 256 + (row & 15) * 16 + h0), pack8(v0, v1)); } } }
;     ...
;             PG8_LDA(At, 1, 1); PG8_STAGE(PG8_SB(1, 0), b3, voffB); PG8_STAGE(PG8_SB(1, 1), b3 + hB, voffB); PG8_STAGE(PG8_SA(1, 0), a3, voffA);
;             PG8_WAIT_V(8); PG8_WAIT_L(0); PG8_BAR; PG8_MMA(1, 0, At, B0); PG8_MMA(1, 1, At, B1); PG8_BAR; PG8_SCHED;
	s_setprio 1
	s_waitcnt lgkmcnt(0)
	v_mfma_f32_16x16x32_bf16 v[60:63], v[132:135], v[188:191], v[60:63]
	v_mfma_f32_16x16x32_bf16 v[56:59], v[140:143], v[188:191], v[56:59]
	v_mfma_f32_16x16x32_bf16 v[44:47], v[132:135], v[208:211], v[44:47]
	v_mfma_f32_16x16x32_bf16 v[40:43], v[140:143], v[208:211], v[40:43]
	v_mfma_f32_16x16x32_bf16 v[28:31], v[132:135], v[230:233], v[28:31]
	v_mfma_f32_16x16x32_bf16 v[24:27], v[140:143], v[230:233], v[24:27]
	v_mfma_f32_16x16x32_bf16 v[12:15], v[132:135], v[238:241], v[12:15]
	v_mfma_f32_16x16x32_bf16 v[8:11], v[140:143], v[238:241], v[8:11]
	v_mfma_f32_16x16x32_bf16 v[60:63], v[136:139], v[200:203], v[60:63]
	v_mfma_f32_16x16x32_bf16 v[56:59], v[144:147], v[200:203], v[56:59]
	v_mfma_f32_16x16x32_bf16 v[44:47], v[136:139], v[214:217], v[44:47]
	v_mfma_f32_16x16x32_bf16 v[40:43], v[144:147], v[214:217], v[40:43]
	v_mfma_f32_16x16x32_bf16 v[28:31], v[136:139], v[234:237], v[28:31]
	v_mfma_f32_16x16x32_bf16 v[24:27], v[144:147], v[234:237], v[24:27]
	v_mfma_f32_16x16x32_bf16 v[12:15], v[136:139], v[242:245], v[12:15]
	v_mfma_f32_16x16x32_bf16 v[8:11], v[144:147], v[242:245], v[8:11]
	s_setprio 0
	s_setprio 1
	s_waitcnt vmcnt(4)
	v_add_f32_e32 v246, v246, v247
	v_add_f32_e32 v248, v248, v249
	v_add_f32_e32 v246, v246, v248
	v_mov_b32_e32 v206, v246
	s_nop 1
	v_permlane16_swap_b32_e32 v246, v206
	v_add_f32_e32 v246, v246, v206
	v_mov_b32_e32 v206, v246
	s_nop 1
	v_permlane32_swap_b32_e32 v246, v206
	v_add_f32_e32 v246, v246, v206
	v_fmamk_f32 v246, v246, 0x3a800000, v251
	v_rsq_f32_e32 v199, v246
	v_add_f32_e32 v128, v128, v129
	v_add_f32_e32 v130, v130, v131
	v_add_f32_e32 v128, v128, v130
	v_mov_b32_e32 v206, v128
	s_nop 1
	v_permlane16_swap_b32_e32 v128, v206
	v_add_f32_e32 v128, v128, v206
	v_mov_b32_e32 v206, v128
	s_nop 1
	v_permlane32_swap_b32_e32 v128, v206
	v_add_f32_e32 v128, v128, v206
	v_fmamk_f32 v128, v128, 0x3a800000, v251
	v_rsq_f32_e32 v212, v128
	v_mfma_f32_16x16x32_bf16 v[52:55], v[148:151], v[188:191], v[52:55]
	v_mul_f32_e32 v80, v199, v80
	v_max_f32_e32 v80, 0, v80
	v_mul_f32_e32 v80, v80, v80
	v_mul_f32_e32 v81, v199, v81
	v_max_f32_e32 v81, 0, v81
	v_mul_f32_e32 v81, v81, v81
	v_mul_f32_e32 v82, v199, v82
	v_max_f32_e32 v82, 0, v82
	v_mul_f32_e32 v82, v82, v82
	v_mul_f32_e32 v83, v199, v83
	v_mfma_f32_16x16x32_bf16 v[48:51], v[180:183], v[188:191], v[48:51]
	v_max_f32_e32 v83, 0, v83
	v_mul_f32_e32 v83, v83, v83
	v_mul_f32_e32 v84, v199, v84
	v_max_f32_e32 v84, 0, v84
	v_mul_f32_e32 v84, v84, v84
	v_mul_f32_e32 v85, v199, v85
	v_max_f32_e32 v85, 0, v85
	v_mul_f32_e32 v85, v85, v85
	v_mul_f32_e32 v86, v199, v86
	v_max_f32_e32 v86, 0, v86
	v_mfma_f32_16x16x32_bf16 v[36:39], v[148:151], v[208:211], v[36:39]
	v_mul_f32_e32 v86, v86, v86
	v_mul_f32_e32 v87, v199, v87
	v_max_f32_e32 v87, 0, v87
	v_mul_f32_e32 v87, v87, v87
	v_mul_f32_e32 v88, v199, v88
	v_max_f32_e32 v88, 0, v88
	v_mul_f32_e32 v88, v88, v88
	v_mul_f32_e32 v89, v199, v89
	v_max_f32_e32 v89, 0, v89
	v_mul_f32_e32 v89, v89, v89
	v_mfma_f32_16x16x32_bf16 v[32:35], v[180:183], v[208:211], v[32:35]
	v_mul_f32_e32 v90, v199, v90
	v_max_f32_e32 v90, 0, v90
	v_mul_f32_e32 v90, v90, v90
	v_mul_f32_e32 v91, v199, v91
	v_max_f32_e32 v91, 0, v91
	v_mul_f32_e32 v91, v91, v91
	v_mul_f32_e32 v92, v199, v92
	v_max_f32_e32 v92, 0, v92
	v_mul_f32_e32 v92, v92, v92
	v_mul_f32_e32 v93, v199, v93
	v_mfma_f32_16x16x32_bf16 v[20:23], v[148:151], v[230:233], v[20:23]
	v_max_f32_e32 v93, 0, v93
	v_mul_f32_e32 v93, v93, v93
	v_mul_f32_e32 v94, v199, v94
	v_max_f32_e32 v94, 0, v94
	v_mul_f32_e32 v94, v94, v94
	v_mul_f32_e32 v95, v199, v95
	v_max_f32_e32 v95, 0, v95
	v_mul_f32_e32 v95, v95, v95
	v_cvt_pk_bf16_f32 v92, v92, v93
	v_mfma_f32_16x16x32_bf16 v[16:19], v[180:183], v[230:233], v[16:19]
	v_cvt_pk_bf16_f32 v93, v94, v95
	v_cvt_pk_bf16_f32 v94, v88, v89
	v_cvt_pk_bf16_f32 v95, v90, v91
	v_mfma_f32_16x16x32_bf16 v[4:7], v[148:151], v[238:241], v[4:7]
	global_store_dwordx4 v207, v[92:95], s[24:25] nt
	v_cvt_pk_bf16_f32 v84, v84, v85
	v_cvt_pk_bf16_f32 v85, v86, v87
	v_cvt_pk_bf16_f32 v86, v80, v81
	v_mfma_f32_16x16x32_bf16 v[0:3], v[180:183], v[238:241], v[0:3]
	v_cvt_pk_bf16_f32 v87, v82, v83
	global_store_dwordx4 v207, v[84:87], s[24:25] offset:256 nt
	v_add_u32_e32 v207, 0x20000, v207
	v_mul_f32_e32 v64, v212, v64
	v_max_f32_e32 v64, 0, v64
	v_mul_f32_e32 v64, v64, v64
	v_mul_f32_e32 v65, v212, v65
	v_max_f32_e32 v65, 0, v65
	v_mfma_f32_16x16x32_bf16 v[52:55], v[176:179], v[200:203], v[52:55]
	v_mul_f32_e32 v65, v65, v65
	v_mul_f32_e32 v66, v212, v66
	v_max_f32_e32 v66, 0, v66
	v_mul_f32_e32 v66, v66, v66
	v_mul_f32_e32 v67, v212, v67
	v_max_f32_e32 v67, 0, v67
	v_mul_f32_e32 v67, v67, v67
	v_mul_f32_e32 v68, v212, v68
	v_max_f32_e32 v68, 0, v68
	v_mul_f32_e32 v68, v68, v68
	v_mfma_f32_16x16x32_bf16 v[48:51], v[184:187], v[200:203], v[48:51]
	v_mul_f32_e32 v69, v212, v69
	v_max_f32_e32 v69, 0, v69
	v_mul_f32_e32 v69, v69, v69
	v_mul_f32_e32 v70, v212, v70
	v_max_f32_e32 v70, 0, v70
	v_mul_f32_e32 v70, v70, v70
	v_mul_f32_e32 v71, v212, v71
	v_max_f32_e32 v71, 0, v71
	v_mul_f32_e32 v71, v71, v71
	v_mul_f32_e32 v72, v212, v72
	v_mfma_f32_16x16x32_bf16 v[36:39], v[176:179], v[214:217], v[36:39]
	v_max_f32_e32 v72, 0, v72
	v_mul_f32_e32 v72, v72, v72
	v_mul_f32_e32 v73, v212, v73
	v_max_f32_e32 v73, 0, v73
	v_mul_f32_e32 v73, v73, v73
	v_mul_f32_e32 v74, v212, v74
	v_max_f32_e32 v74, 0, v74
	v_mul_f32_e32 v74, v74, v74
	v_mul_f32_e32 v75, v212, v75
	v_max_f32_e32 v75, 0, v75
	v_mfma_f32_16x16x32_bf16 v[32:35], v[184:187], v[214:217], v[32:35]
	v_mul_f32_e32 v75, v75, v75
	v_mul_f32_e32 v76, v212, v76
	v_max_f32_e32 v76, 0, v76
	v_mul_f32_e32 v76, v76, v76
	v_mul_f32_e32 v77, v212, v77
	v_max_f32_e32 v77, 0, v77
	v_mul_f32_e32 v77, v77, v77
	v_mul_f32_e32 v78, v212, v78
	v_max_f32_e32 v78, 0, v78
	v_mul_f32_e32 v78, v78, v78
	v_mfma_f32_16x16x32_bf16 v[20:23], v[176:179], v[234:237], v[20:23]
	v_mul_f32_e32 v79, v212, v79
	v_max_f32_e32 v79, 0, v79
	v_mul_f32_e32 v79, v79, v79
	v_cvt_pk_bf16_f32 v76, v76, v77
	v_cvt_pk_bf16_f32 v77, v78, v79
	v_mfma_f32_16x16x32_bf16 v[16:19], v[184:187], v[234:237], v[16:19]
	v_cvt_pk_bf16_f32 v78, v72, v73
	v_cvt_pk_bf16_f32 v79, v74, v75
	global_store_dwordx4 v207, v[76:79], s[24:25] nt
	v_cvt_pk_bf16_f32 v68, v68, v69
	v_mfma_f32_16x16x32_bf16 v[4:7], v[176:179], v[242:245], v[4:7]
	v_cvt_pk_bf16_f32 v69, v70, v71
	v_cvt_pk_bf16_f32 v70, v64, v65
	v_cvt_pk_bf16_f32 v71, v66, v67
	global_store_dwordx4 v207, v[68:71], s[24:25] offset:256 nt
	v_add_u32_e32 v207, 0x20000, v207
	v_mfma_f32_16x16x32_bf16 v[0:3], v[184:187], v[242:245], v[0:3]
	s_setprio 0
	s_barrier
	s_branch .Lup_after_loop
